# GQA main loop head aligned to a 256-byte boundary
# speedup vs baseline: 1.0086x; 1.0086x over previous
.LBB0_706:
	s_mul_hi_i32 s0, s14, 0x2aaaaaab
	s_lshr_b32 s1, s0, 31
	s_ashr_i32 s0, s0, 5
	s_add_i32 s0, s0, s1
	s_mul_i32 s1, s0, 0xc0
	s_sub_i32 s1, s14, s1
	s_and_b32 s2, s1, 3
	s_bfe_u32 s4, s1, 0x10002
	s_mul_i32 s2, s2, 24
	s_ashr_i32 s1, s1, 3
	s_add_i32 s5, s2, s1
	s_bfe_i32 s2, s5, 0x80000
	s_bfe_u32 s2, s2, 0x5000a
	s_add_i32 s2, s5, s2
	s_bfe_i32 s2, s2, 0x80000
	s_mul_i32 s1, s4, 3
	s_bfe_u32 s2, s2, 0x80005
	s_add_i32 s6, s1, s2
	s_ashr_i32 s1, s0, 31
	s_lshl_b64 s[2:3], s[0:1], 13
	s_lshl_b32 s1, s5, 8
	s_and_b32 s1, s1, 0x1f00
	s_or_b32 s2, s2, s1
	s_mul_hi_u32 s5, s2, 0xe00
	s_mul_i32 s7, s3, 0xe00
	s_mul_i32 s1, s2, 0xe00
	s_add_i32 s5, s5, s7
	v_readlane_b32 s8, v254, 35
	v_readlane_b32 s9, v254, 36
	s_add_u32 s1, s8, s1
	s_addc_u32 s5, s9, s5
	s_lshl_b32 s16, s6, 6
	s_lshl_b32 s6, s6, 7
	s_add_u32 s1, s1, s6
	s_addc_u32 s5, s5, 0
	s_lshl_b32 s4, s4, 7
	s_add_u32 s6, s10, s4
	s_addc_u32 s7, s11, 0
	v_mov_b32_e32 v42, v191
	s_add_u32 s18, s12, s4
	s_addc_u32 s19, s13, 0
	v_readfirstlane_b32 s17, v42
	s_ashr_i32 s15, s17, 6
	s_lshl_b32 s8, s0, 8
	s_lshl_b32 s36, s15, 5
	s_lshl_b32 s9, s0, 13
	s_add_i32 s20, s8, 0x4000
	v_and_b32_e32 v189, 63, v42
	s_ashr_i32 s37, s36, 31
	s_mul_i32 s0, s15, 0x1c000
	s_mul_hi_i32 s4, s36, 0xe00
	s_add_u32 s22, s1, s0
	v_mul_u32_u24_e32 v0, 0x700, v189
	s_addc_u32 s23, s5, s4
	v_lshlrev_b32_e32 v0, 1, v0
	s_lshl_b32 s0, s15, 3
	v_lshl_add_u64 v[2:3], s[6:7], 0, v[0:1]
	s_ashr_i32 s1, s0, 31
	v_lshl_add_u64 v[192:193], s[0:1], 1, v[2:3]
	s_lshl_b32 s0, s15, 4
	v_bfe_u32 v0, v42, 2, 4
	v_and_or_b32 v0, s0, 48, v0
	v_mul_u32_u24_e32 v0, 0x700, v0
	s_ashr_i32 s0, s17, 3
	v_lshlrev_b32_e32 v0, 1, v0
	s_andn2_b32 s0, s0, 31
	v_lshl_add_u64 v[2:3], s[18:19], 0, v[0:1]
	s_ashr_i32 s1, s0, 31
	v_lshlrev_b32_e32 v198, 3, v42
	s_and_b32 s4, s17, 0x3fffffc0
	v_lshl_add_u64 v[2:3], s[0:1], 1, v[2:3]
	v_and_b32_e32 v201, 24, v198
	s_lshl_b32 s0, s15, 10
	v_lshlrev_b32_e32 v0, 1, v201
	s_cmp_lg_u32 0, -1
	v_lshl_add_u64 v[194:195], v[2:3], 0, v[0:1]
	s_cselect_b32 s1, 0, 0
	v_and_b32_e32 v199, 31, v42
	v_bfe_u32 v200, v42, 5, 1
	s_add_i32 s18, s0, s1
	v_mad_i64_i32 v[2:3], s[0:1], s9, v217, v[192:193]
	s_mov_b32 m0, s18
	s_nop 0
	global_load_lds_dwordx4 v[2:3], off
	s_add_i32 s19, s18, 0x6000
	v_mad_i64_i32 v[82:83], s[0:1], s9, v217, v[194:195]
	s_mov_b32 m0, s19
	s_nop 0
	global_load_lds_dwordx4 v[82:83], off
	s_or_b32 s1, s9, 64
	v_mul_u32_u24_e32 v0, 0x700, v199
	v_lshlrev_b32_e32 v203, 4, v200
	v_mad_i64_i32 v[2:3], s[6:7], s1, v217, v[192:193]
	s_add_i32 s0, s18, 0x2000
	s_mov_b32 m0, s0
	s_nop 0
	global_load_lds_dwordx4 v[2:3], off
	v_lshl_or_b32 v0, v0, 1, v203
	global_load_dwordx4 v[142:145], v0, s[22:23]
	global_load_dwordx4 v[138:141], v0, s[22:23] offset:32
	global_load_dwordx4 v[130:133], v0, s[22:23] offset:64
	global_load_dwordx4 v[122:125], v0, s[22:23] offset:96
	v_lshlrev_b32_e32 v2, 10, v200
	v_lshlrev_b32_e32 v3, 4, v199
	v_add3_u32 v206, 0, v2, v3
	v_mov_b32_e32 v2, v1
	v_mov_b32_e32 v3, v1
	v_mov_b32_e32 v4, v1
	v_mov_b32_e32 v5, v1
	v_mov_b32_e32 v6, v1
	v_mov_b32_e32 v7, v1
	v_mov_b32_e32 v8, v1
	v_mov_b32_e32 v9, v1
	v_mov_b32_e32 v10, v1
	v_mov_b32_e32 v11, v1
	v_mov_b32_e32 v12, v1
	v_mov_b32_e32 v13, v1
	v_mov_b32_e32 v14, v1
	v_mov_b32_e32 v15, v1
	v_mov_b32_e32 v0, v1
	v_mov_b64_e32 v[16:17], v[14:15]
	v_mov_b64_e32 v[14:15], v[12:13]
	v_mov_b64_e32 v[12:13], v[10:11]
	v_mov_b64_e32 v[10:11], v[8:9]
	v_mov_b64_e32 v[8:9], v[6:7]
	v_mov_b64_e32 v[6:7], v[4:5]
	v_mov_b64_e32 v[4:5], v[2:3]
	v_mov_b64_e32 v[2:3], v[0:1]
	s_or_b32 s0, s9, 0x80
	v_mad_i64_i32 v[18:19], s[6:7], s0, v217, v[192:193]
	s_add_i32 s0, s18, 0x4000
	s_mov_b32 m0, s0
	s_nop 0
	global_load_lds_dwordx4 v[18:19], off
	s_waitcnt vmcnt(3) lgkmcnt(0)
	s_barrier
	ds_read_b128 v[34:37], v206
	ds_read_b128 v[38:41], v206 offset:512
	s_waitcnt vmcnt(3) lgkmcnt(1)
	v_mfma_f32_32x32x16_bf16 v[18:33], v[34:37], v[142:145], v[2:17]
	v_lshlrev_b32_e32 v0, 1, v42
	v_and_b32_e32 v202, 32, v0
	v_lshlrev_b32_e32 v0, 4, v42
	s_lshl_b32 s4, s4, 2
	s_add_i32 s17, s4, 0
	s_or_b32 s4, s9, 0xc0
	v_and_b32_e32 v0, 0xc0, v0
	s_waitcnt lgkmcnt(0)
	v_mfma_f32_32x32x16_bf16 v[2:17], v[38:41], v[142:145], v[2:17]
	ds_read_b128 v[34:37], v206 offset:2048
	ds_read_b128 v[38:41], v206 offset:2560
	v_lshl_or_b32 v0, v200, 8, v0
	v_add_u32_e32 v84, 0, v202
	v_mov_b32_e32 v224, 0
	s_movk_i32 s21, 0x4000
	s_mov_b32 s23, -1
	s_mov_b32 s0, 0
	s_waitcnt vmcnt(2) lgkmcnt(1)
	v_mfma_f32_32x32x16_bf16 v[18:33], v[34:37], v[138:141], v[18:33]
	s_movk_i32 s24, 0x2000
	v_add3_u32 v207, v84, v201, v0
	v_cmp_gt_u32_e64 s[40:41], 32, v189
	v_lshl_add_u32 v204, v199, 2, s17
	v_lshl_add_u64 v[196:197], v[82:83], 0, s[28:29]
	s_waitcnt lgkmcnt(0)
	v_mfma_f32_32x32x16_bf16 v[2:17], v[38:41], v[138:141], v[2:17]
	ds_read_b128 v[34:37], v206 offset:4096
	ds_read_b128 v[38:41], v206 offset:4608
	s_waitcnt vmcnt(1) lgkmcnt(1)
	v_mfma_f32_32x32x16_bf16 v[18:33], v[34:37], v[130:133], v[18:33]
	s_waitcnt lgkmcnt(0)
	v_mfma_f32_32x32x16_bf16 v[2:17], v[38:41], v[130:133], v[2:17]
	ds_read_b128 v[34:37], v206 offset:6144
	ds_read_b128 v[38:41], v206 offset:6656
	s_waitcnt vmcnt(0) lgkmcnt(1)
	v_mfma_f32_32x32x16_bf16 v[18:33], v[34:37], v[122:125], v[18:33]
	s_waitcnt lgkmcnt(0)
	v_mfma_f32_32x32x16_bf16 v[2:17], v[38:41], v[122:125], v[2:17]
	s_nop 15
	s_nop 7
	s_nop 0
	v_max3_f32 v34, v18, v19, v2
	v_max3_f32 v35, v20, v21, v3
	s_nop 0
	v_max3_f32 v34, v34, v4, v5
	v_max3_f32 v35, v35, v24, v25
	s_nop 0
	v_max3_f32 v34, v34, v22, v23
	v_max3_f32 v35, v35, v8, v9
	s_nop 0
	v_max3_f32 v34, v34, v6, v7
	v_max3_f32 v35, v35, v28, v29
	s_nop 0
	v_max3_f32 v34, v34, v26, v27
	v_max3_f32 v35, v35, v12, v13
	s_nop 0
	v_max3_f32 v34, v34, v10, v11
	v_max3_f32 v35, v35, v32, v33
	s_nop 0
	v_max3_f32 v34, v34, v30, v31
	v_max3_f32 v35, v35, v16, v17
	s_nop 0
	v_max3_f32 v34, v34, v14, v15
	s_nop 0
	v_max_f32_e32 v34, v34, v35
	s_nop 0
	v_mov_b32_e32 v35, v34
	s_nop 1
	v_permlane32_swap_b32_e32 v34, v35
	v_max_f32_e32 v34, v34, v35
	s_nop 0
	v_add_f32_e32 v205, v1, v34
	v_sub_f32_e32 v18, v18, v34
	v_sub_f32_e32 v2, v2, v34
	v_sub_f32_e32 v19, v19, v34
	v_sub_f32_e32 v3, v3, v34
	v_sub_f32_e32 v20, v20, v34
	v_sub_f32_e32 v4, v4, v34
	v_sub_f32_e32 v21, v21, v34
	v_sub_f32_e32 v5, v5, v34
	v_sub_f32_e32 v22, v22, v34
	v_sub_f32_e32 v6, v6, v34
	v_sub_f32_e32 v23, v23, v34
	v_sub_f32_e32 v7, v7, v34
	v_sub_f32_e32 v24, v24, v34
	v_sub_f32_e32 v8, v8, v34
	v_sub_f32_e32 v25, v25, v34
	v_sub_f32_e32 v9, v9, v34
	v_sub_f32_e32 v26, v26, v34
	v_sub_f32_e32 v10, v10, v34
	v_sub_f32_e32 v27, v27, v34
	v_sub_f32_e32 v11, v11, v34
	v_sub_f32_e32 v28, v28, v34
	v_sub_f32_e32 v12, v12, v34
	v_sub_f32_e32 v29, v29, v34
	v_sub_f32_e32 v13, v13, v34
	v_sub_f32_e32 v30, v30, v34
	v_sub_f32_e32 v14, v14, v34
	v_sub_f32_e32 v31, v31, v34
	v_sub_f32_e32 v15, v15, v34
	v_sub_f32_e32 v32, v32, v34
	v_sub_f32_e32 v16, v16, v34
	v_sub_f32_e32 v33, v33, v34
	v_sub_f32_e32 v17, v17, v34
	s_nop 0
	v_xor_b32_e32 v34, 0x80000000, v205
	v_mov_b32_e32 v35, v34
	v_mov_b32_e32 v36, v34
	v_mov_b32_e32 v37, v34
	v_mov_b32_e32 v38, v34
	v_mov_b32_e32 v39, v34
	v_mov_b32_e32 v40, v34
	v_mov_b32_e32 v41, v34
	v_mov_b32_e32 v42, v34
	v_mov_b32_e32 v43, v34
	v_mov_b32_e32 v44, v34
	v_mov_b32_e32 v45, v34
	v_mov_b32_e32 v46, v34
	v_mov_b32_e32 v47, v34
	v_mov_b32_e32 v48, v34
	v_mov_b32_e32 v49, v34
	s_waitcnt vmcnt(0) lgkmcnt(0)
	s_barrier
	v_exp_f32_e32 v50, v2
	v_exp_f32_e32 v51, v3
	v_mad_i64_i32 v[2:3], s[4:5], s4, v217, v[192:193]
	s_mov_b32 m0, s18
	s_nop 0
	global_load_lds_dwordx4 v[2:3], off
	v_exp_f32_e32 v66, v18
	v_mad_i64_i32 v[2:3], s[4:5], s1, v217, v[194:195]
	s_add_i32 s1, s18, 0x8000
	s_mov_b32 m0, s1
	s_nop 0
	global_load_lds_dwordx4 v[2:3], off
	ds_read_b128 v[174:177], v206 offset:8192
	ds_read_b128 v[170:173], v206 offset:8704
	ds_read_b128 v[166:169], v206 offset:10240
	ds_read_b128 v[162:165], v206 offset:10752
	ds_read_b128 v[158:161], v206 offset:12288
	ds_read_b128 v[154:157], v206 offset:12800
	ds_read_b128 v[150:153], v206 offset:14336
	ds_read_b128 v[146:149], v206 offset:14848
	v_exp_f32_e32 v67, v19
	v_exp_f32_e32 v68, v20
	v_exp_f32_e32 v69, v21
	v_exp_f32_e32 v70, v22
	v_exp_f32_e32 v71, v23
	v_exp_f32_e32 v72, v24
	v_exp_f32_e32 v73, v25
	v_exp_f32_e32 v74, v26
	v_exp_f32_e32 v75, v27
	v_exp_f32_e32 v76, v28
	v_exp_f32_e32 v77, v29
	v_exp_f32_e32 v78, v30
	v_exp_f32_e32 v79, v31
	v_exp_f32_e32 v80, v32
	v_exp_f32_e32 v81, v33
	v_exp_f32_e32 v52, v4
	v_exp_f32_e32 v53, v5
	v_exp_f32_e32 v54, v6
	v_exp_f32_e32 v55, v7
	v_exp_f32_e32 v56, v8
	v_exp_f32_e32 v57, v9
	v_exp_f32_e32 v58, v10
	v_exp_f32_e32 v59, v11
	v_exp_f32_e32 v60, v12
	v_exp_f32_e32 v61, v13
	v_exp_f32_e32 v62, v14
	v_exp_f32_e32 v63, v15
	v_exp_f32_e32 v64, v16
	v_exp_f32_e32 v65, v17
	s_waitcnt vmcnt(2) lgkmcnt(0)
	s_barrier
	v_mov_b32_e32 v2, 0
	v_mov_b32_e32 v3, v224
	v_mov_b32_e32 v4, v224
	v_mov_b32_e32 v5, v224
	v_mov_b32_e32 v6, v224
	v_mov_b32_e32 v7, v224
	v_mov_b32_e32 v8, v224
	v_mov_b32_e32 v9, v224
	v_mov_b32_e32 v10, v224
	v_mov_b32_e32 v11, v224
	v_mov_b32_e32 v12, v224
	v_mov_b32_e32 v13, v224
	v_mov_b32_e32 v14, v224
	v_mov_b32_e32 v15, v224
	v_mov_b32_e32 v16, v224
	v_mov_b32_e32 v17, v224
	v_mov_b32_e32 v18, 0
	v_mov_b32_e32 v19, v224
	v_mov_b32_e32 v20, v224
	v_mov_b32_e32 v21, v224
	v_mov_b32_e32 v22, v224
	v_mov_b32_e32 v23, v224
	v_mov_b32_e32 v24, v224
	v_mov_b32_e32 v25, v224
	v_mov_b32_e32 v26, v224
	v_mov_b32_e32 v27, v224
	v_mov_b32_e32 v28, v224
	v_mov_b32_e32 v29, v224
	v_mov_b32_e32 v30, v224
	v_mov_b32_e32 v31, v224
	v_mov_b32_e32 v32, v224
	v_mov_b32_e32 v33, v224
	.p2alignl 8, 3212836864
